# v40 plus nt policy on the prologue's once-read f32 source loads
# speedup vs baseline: 1.0036x; 1.0036x over previous
.LBB0_35:
	v_lshrrev_b32_e32 v159, 4, v1
	v_mul_u32_u24_e32 v4, s8, v159
	v_lshlrev_b32_e32 v156, 2, v4
	v_lshlrev_b32_e32 v4, 2, v1
	v_mov_b32_e32 v157, 0
	v_and_b32_e32 v158, 60, v4
	v_lshl_add_u64 v[2:3], v[2:3], 0, v[156:157]
	v_lshlrev_b32_e32 v156, 2, v158
	v_lshl_add_u64 v[2:3], v[2:3], 0, v[156:157]
	s_lshl_b64 s[6:7], s[8:9], 4
	v_lshl_add_u64 v[10:11], v[2:3], 0, s[6:7]
	global_load_dwordx4 v[2:5], v[2:3], off nt
	s_nop 0
	global_load_dwordx4 v[6:9], v[10:11], off nt
	v_lshl_add_u64 v[10:11], v[10:11], 0, s[6:7]
	v_lshl_add_u64 v[18:19], v[10:11], 0, s[6:7]
	global_load_dwordx4 v[10:13], v[10:11], off nt
	s_nop 0
	global_load_dwordx4 v[14:17], v[18:19], off nt
	v_lshl_add_u64 v[18:19], v[18:19], 0, s[6:7]
	v_lshl_add_u64 v[26:27], v[18:19], 0, s[6:7]
	global_load_dwordx4 v[18:21], v[18:19], off nt
	s_nop 0
	global_load_dwordx4 v[22:25], v[26:27], off nt
	v_lshl_add_u64 v[26:27], v[26:27], 0, s[6:7]
	v_lshl_add_u64 v[34:35], v[26:27], 0, s[6:7]
	v_lshl_add_u64 v[38:39], v[34:35], 0, s[6:7]
	v_lshl_add_u64 v[42:43], v[38:39], 0, s[6:7]
	v_lshl_add_u64 v[46:47], v[42:43], 0, s[6:7]
	v_lshl_add_u64 v[50:51], v[46:47], 0, s[6:7]
	v_lshl_add_u64 v[54:55], v[50:51], 0, s[6:7]
	v_lshl_add_u64 v[58:59], v[54:55], 0, s[6:7]
	v_lshl_add_u64 v[62:63], v[58:59], 0, s[6:7]
	global_load_dwordx4 v[26:29], v[26:27], off nt
	s_nop 0
	global_load_dwordx4 v[30:33], v[34:35], off nt
	v_and_b32_e32 v66, 7, v66
	global_load_dwordx4 v[34:37], v[38:39], off nt
	v_lshrrev_b32_e32 v164, 3, v1
	global_load_dwordx4 v[38:41], v[42:43], off nt
	s_lshl_b32 s8, s2, 7
	global_load_dwordx4 v[42:45], v[46:47], off nt
	s_lshl_b32 s9, s50, 4
	global_load_dwordx4 v[46:49], v[50:51], off nt
	v_lshlrev_b32_e32 v162, 3, v66
	global_load_dwordx4 v[50:53], v[54:55], off nt
	v_mul_u32_u24_e32 v66, 0x820, v66
	global_load_dwordx4 v[54:57], v[58:59], off nt
	v_lshlrev_b32_e32 v69, 2, v164
	global_load_dwordx4 v[58:61], v[62:63], off nt
	v_lshl_add_u64 v[62:63], v[62:63], 0, s[6:7]
	global_load_dwordx4 v[62:65], v[62:63], off nt
	s_mul_i32 s6, s50, 0x4100
	s_add_i32 s6, s6, 0
	s_add_i32 s59, s8, s9
	s_lshl_b32 s8, s2, 15
	s_lshl_b32 s9, s50, 12
	v_add_u32_e32 v67, s6, v156
	v_mul_u32_u24_e32 v68, 0x104, v159
	v_add3_u32 v163, s6, v66, v69
	s_lshl_b32 s6, s50, 5
	s_lshl_b32 s56, s82, 10
	s_lshl_b32 s7, s50, 6
	s_lshl_b32 s58, s82, 8
	s_add_i32 s8, s8, s9
	s_mov_b32 s45, 0
	v_or_b32_e32 v166, 8, v164
	v_or_b32_e32 v168, 16, v164
	v_or_b32_e32 v170, 24, v164
	v_or_b32_e32 v172, 32, v164
	v_or_b32_e32 v174, 40, v164
	v_or_b32_e32 v176, 48, v164
	v_or_b32_e32 v178, 56, v164
	s_bfe_u32 s51, s48, 0x20006
	s_lshl_b32 s52, s82, 4
	s_lshl_b32 s53, s2, 8
	s_add_i32 s54, s14, s6
	s_lshl_b32 s55, s2, 9
	s_add_i32 s57, s56, s7
	s_lshl_b32 s60, s82, 16
	s_add_i32 s61, s8, 0xef800000
	s_add_i32 s62, s58, s6
	s_add_i32 s63, s14, s7
	s_lshl_b32 s64, s82, 7
	s_lshl_b32 s65, s82, 15
	s_movk_i32 s66, 0x60
	s_movk_i32 s67, 0xb0
	v_mov_b32_e32 v165, 0x2c00000
	v_add_u32_e32 v167, v67, v68
	v_mov_b32_e32 v220, v157
	v_mov_b32_e32 v221, v157
	v_mov_b32_e32 v222, v157
	v_mov_b32_e32 v223, v157
	s_mov_b32 s70, s47
	s_mov_b32 s69, s46
	v_mov_b64_e32 v[186:187], v[160:161]
	v_mov_b64_e32 v[188:189], v[182:183]
	v_mov_b64_e32 v[190:191], v[180:181]
	v_mov_b64_e32 v[184:185], v[154:155]
	s_mov_b32 s71, s15
	s_branch .LBB0_39

.LBB0_65:
	v_mul_u32_u24_e32 v68, s6, v159
	v_lshlrev_b32_e32 v156, 2, v68
	v_lshl_add_u64 v[66:67], v[66:67], 0, v[156:157]
	v_lshlrev_b32_e32 v156, 2, v158
	v_lshl_add_u64 v[66:67], v[66:67], 0, v[156:157]
	s_lshl_b64 s[6:7], s[6:7], 4
	v_lshl_add_u64 v[74:75], v[66:67], 0, s[6:7]
	global_load_dwordx4 v[70:73], v[66:67], off nt
	s_nop 0
	global_load_dwordx4 v[66:69], v[74:75], off nt
	v_lshl_add_u64 v[74:75], v[74:75], 0, s[6:7]
	v_lshl_add_u64 v[82:83], v[74:75], 0, s[6:7]
	global_load_dwordx4 v[78:81], v[74:75], off nt
	s_nop 0
	global_load_dwordx4 v[74:77], v[82:83], off nt
	v_lshl_add_u64 v[82:83], v[82:83], 0, s[6:7]
	v_lshl_add_u64 v[90:91], v[82:83], 0, s[6:7]
	global_load_dwordx4 v[86:89], v[82:83], off nt
	s_nop 0
	global_load_dwordx4 v[82:85], v[90:91], off nt
	v_lshl_add_u64 v[90:91], v[90:91], 0, s[6:7]
	v_lshl_add_u64 v[98:99], v[90:91], 0, s[6:7]
	v_lshl_add_u64 v[102:103], v[98:99], 0, s[6:7]
	v_lshl_add_u64 v[106:107], v[102:103], 0, s[6:7]
	v_lshl_add_u64 v[110:111], v[106:107], 0, s[6:7]
	v_lshl_add_u64 v[114:115], v[110:111], 0, s[6:7]
	v_lshl_add_u64 v[118:119], v[114:115], 0, s[6:7]
	v_lshl_add_u64 v[122:123], v[118:119], 0, s[6:7]
	v_lshl_add_u64 v[126:127], v[122:123], 0, s[6:7]
	global_load_dwordx4 v[94:97], v[90:91], off nt
	s_nop 0
	global_load_dwordx4 v[90:93], v[98:99], off nt
	s_nop 0
	global_load_dwordx4 v[98:101], v[102:103], off nt
	s_nop 0
	global_load_dwordx4 v[102:105], v[106:107], off nt
	s_nop 0
	global_load_dwordx4 v[106:109], v[110:111], off nt
	s_nop 0
	global_load_dwordx4 v[110:113], v[114:115], off nt
	s_nop 0
	global_load_dwordx4 v[114:117], v[118:119], off nt
	s_nop 0
	global_load_dwordx4 v[118:121], v[122:123], off nt
	s_nop 0
	global_load_dwordx4 v[122:125], v[126:127], off nt
	v_lshl_add_u64 v[126:127], v[126:127], 0, s[6:7]
	global_load_dwordx4 v[126:129], v[126:127], off nt
.LBB0_66:
	v_cmp_ne_u64_e32 vcc, 0, v[180:181]
	s_cmp_eq_u32 s47, 0
	v_add_u32_e32 v169, 0x410, v167
	v_cndmask_b32_e64 v130, 0, 1, vcc
	v_add_u32_e32 v171, 0x418, v167
	v_add_u32_e32 v173, 0x820, v167
	v_add_u32_e32 v175, 0x828, v167
	v_add_u32_e32 v177, 0xc30, v167
	v_add_u32_e32 v179, 0xc38, v167
	v_add_u32_e32 v194, 0x1040, v167
	v_add_u32_e32 v195, 0x1048, v167
	v_add_u32_e32 v196, 0x1450, v167
	v_add_u32_e32 v197, 0x1458, v167
	v_add_u32_e32 v198, 0x1860, v167
	v_add_u32_e32 v199, 0x1868, v167
	v_add_u32_e32 v200, 0x1c70, v167
	v_add_u32_e32 v201, 0x1c78, v167
	v_add_u32_e32 v202, 0x2080, v167
	v_add_u32_e32 v203, 0x2088, v167
	v_add_u32_e32 v204, 0x2490, v167
	v_add_u32_e32 v205, 0x2498, v167
	v_add_u32_e32 v206, 0x28a0, v167
	v_add_u32_e32 v207, 0x28a8, v167
	v_add_u32_e32 v208, 0x2cb0, v167
	v_add_u32_e32 v209, 0x2cb8, v167
	v_add_u32_e32 v210, 0x30c0, v167
	v_add_u32_e32 v211, 0x30c8, v167
	v_add_u32_e32 v212, 0x34d0, v167
	v_add_u32_e32 v213, 0x34d8, v167
	v_add_u32_e32 v214, 0x38e0, v167
	v_add_u32_e32 v215, 0x38e8, v167
	v_add_u32_e32 v216, 0x3cf0, v167
	v_add_u32_e32 v217, 0x3cf8, v167
	v_cmp_ne_u32_e64 s[6:7], 1, v130
	s_waitcnt vmcnt(15)
	ds_write2_b32 v167, v2, v3 offset1:1
	ds_write2_b32 v167, v4, v5 offset0:2 offset1:3
	s_waitcnt vmcnt(14)
	ds_write2_b32 v169, v6, v7 offset1:1
	ds_write2_b32 v171, v8, v9 offset1:1
	s_waitcnt vmcnt(13)
	ds_write2_b32 v173, v10, v11 offset1:1
	ds_write2_b32 v175, v12, v13 offset1:1
	s_waitcnt vmcnt(12)
	ds_write2_b32 v177, v14, v15 offset1:1
	ds_write2_b32 v179, v16, v17 offset1:1
	s_waitcnt vmcnt(11)
	ds_write2_b32 v194, v18, v19 offset1:1
	ds_write2_b32 v195, v20, v21 offset1:1
	s_waitcnt vmcnt(10)
	ds_write2_b32 v196, v22, v23 offset1:1
	ds_write2_b32 v197, v24, v25 offset1:1
	s_waitcnt vmcnt(9)
	ds_write2_b32 v198, v26, v27 offset1:1
	ds_write2_b32 v199, v28, v29 offset1:1
	s_waitcnt vmcnt(8)
	ds_write2_b32 v200, v30, v31 offset1:1
	ds_write2_b32 v201, v32, v33 offset1:1
	s_waitcnt vmcnt(7)
	ds_write2_b32 v202, v34, v35 offset1:1
	ds_write2_b32 v203, v36, v37 offset1:1
	s_waitcnt vmcnt(6)
	ds_write2_b32 v204, v38, v39 offset1:1
	ds_write2_b32 v205, v40, v41 offset1:1
	s_waitcnt vmcnt(5)
	ds_write2_b32 v206, v42, v43 offset1:1
	ds_write2_b32 v207, v44, v45 offset1:1
	s_waitcnt vmcnt(4)
	ds_write2_b32 v208, v46, v47 offset1:1
	ds_write2_b32 v209, v48, v49 offset1:1
	s_waitcnt vmcnt(3)
	ds_write2_b32 v210, v50, v51 offset1:1
	ds_write2_b32 v211, v52, v53 offset1:1
	s_waitcnt vmcnt(2)
	ds_write2_b32 v212, v54, v55 offset1:1
	ds_write2_b32 v213, v56, v57 offset1:1
	s_waitcnt vmcnt(1)
	ds_write2_b32 v214, v58, v59 offset1:1
	ds_write2_b32 v215, v60, v61 offset1:1
	s_waitcnt vmcnt(0)
	ds_write2_b32 v216, v62, v63 offset1:1
	ds_write2_b32 v217, v64, v65 offset1:1
	s_cbranch_scc1 .LBB0_75
	s_waitcnt lgkmcnt(0)
	v_mov_b32_e32 v156, 1.0
	s_and_b64 vcc, exec, s[6:7]
	v_mov_b32_e32 v130, 1.0
	v_mov_b32_e32 v131, 1.0
	v_mov_b32_e32 v132, 1.0
	v_mov_b32_e32 v133, 1.0
	v_mov_b32_e32 v134, 1.0
	v_mov_b32_e32 v135, 1.0
	v_mov_b32_e32 v136, 1.0
	v_mov_b32_e32 v137, 1.0
	s_cbranch_vccnz .LBB0_69
	v_lshlrev_b32_e32 v134, 2, v162
	v_readfirstlane_b32 s8, v180
	v_readfirstlane_b32 s9, v181
	s_nop 4
	global_load_dwordx4 v[130:133], v134, s[8:9] offset:16 nt
	s_nop 0
	global_load_dwordx4 v[134:137], v134, s[8:9] nt

.LBB0_110:
	s_waitcnt lgkmcnt(0)
	v_mov_b32_e32 v219, 1.0
	s_and_b64 vcc, exec, s[6:7]
	v_mov_b32_e32 v130, 1.0
	v_mov_b32_e32 v131, 1.0
	v_mov_b32_e32 v132, 1.0
	v_mov_b32_e32 v133, 1.0
	v_mov_b32_e32 v134, 1.0
	v_mov_b32_e32 v135, 1.0
	v_mov_b32_e32 v136, 1.0
	v_mov_b32_e32 v137, 1.0
	s_cbranch_vccnz .LBB0_112
	v_lshlrev_b32_e32 v134, 2, v162
	v_readfirstlane_b32 s6, v180
	v_readfirstlane_b32 s7, v181
	s_nop 4
	global_load_dwordx4 v[130:133], v134, s[6:7] offset:16 nt
	s_nop 0
	global_load_dwordx4 v[134:137], v134, s[6:7] nt

.LBB0_179:
	v_mul_u32_u24_e32 v4, s6, v159
	v_lshlrev_b32_e32 v156, 2, v4
	v_lshl_add_u64 v[2:3], v[2:3], 0, v[156:157]
	v_lshlrev_b32_e32 v156, 2, v158
	v_lshl_add_u64 v[2:3], v[2:3], 0, v[156:157]
	s_lshl_b64 s[6:7], s[6:7], 4
	v_lshl_add_u64 v[10:11], v[2:3], 0, s[6:7]
	global_load_dwordx4 v[2:5], v[2:3], off nt
	s_nop 0
	global_load_dwordx4 v[6:9], v[10:11], off nt
	v_lshl_add_u64 v[10:11], v[10:11], 0, s[6:7]
	v_lshl_add_u64 v[18:19], v[10:11], 0, s[6:7]
	global_load_dwordx4 v[10:13], v[10:11], off nt
	s_nop 0
	global_load_dwordx4 v[14:17], v[18:19], off nt
	v_lshl_add_u64 v[18:19], v[18:19], 0, s[6:7]
	v_lshl_add_u64 v[26:27], v[18:19], 0, s[6:7]
	global_load_dwordx4 v[18:21], v[18:19], off nt
	s_nop 0
	global_load_dwordx4 v[22:25], v[26:27], off nt
	v_lshl_add_u64 v[26:27], v[26:27], 0, s[6:7]
	v_lshl_add_u64 v[34:35], v[26:27], 0, s[6:7]
	v_lshl_add_u64 v[38:39], v[34:35], 0, s[6:7]
	v_lshl_add_u64 v[42:43], v[38:39], 0, s[6:7]
	v_lshl_add_u64 v[46:47], v[42:43], 0, s[6:7]
	v_lshl_add_u64 v[50:51], v[46:47], 0, s[6:7]
	v_lshl_add_u64 v[54:55], v[50:51], 0, s[6:7]
	v_lshl_add_u64 v[58:59], v[54:55], 0, s[6:7]
	v_lshl_add_u64 v[62:63], v[58:59], 0, s[6:7]
	global_load_dwordx4 v[26:29], v[26:27], off nt
	s_nop 0
	global_load_dwordx4 v[30:33], v[34:35], off nt
	s_nop 0
	global_load_dwordx4 v[34:37], v[38:39], off nt
	s_nop 0
	global_load_dwordx4 v[38:41], v[42:43], off nt
	s_nop 0
	global_load_dwordx4 v[42:45], v[46:47], off nt
	s_nop 0
	global_load_dwordx4 v[46:49], v[50:51], off nt
	s_nop 0
	global_load_dwordx4 v[50:53], v[54:55], off nt
	s_nop 0
	global_load_dwordx4 v[54:57], v[58:59], off nt
	s_nop 0
	global_load_dwordx4 v[58:61], v[62:63], off nt
	v_lshl_add_u64 v[62:63], v[62:63], 0, s[6:7]
	global_load_dwordx4 v[62:65], v[62:63], off nt
.LBB0_180:
	v_cmp_ne_u64_e32 vcc, 0, v[190:191]
	s_cmp_eq_u32 s70, 0
	ds_write2_b32 v167, v70, v71 offset1:1
	ds_write2_b32 v167, v72, v73 offset0:2 offset1:3
	ds_write2_b32 v169, v66, v67 offset1:1
	ds_write2_b32 v171, v68, v69 offset1:1
	ds_write2_b32 v173, v78, v79 offset1:1
	ds_write2_b32 v175, v80, v81 offset1:1
	ds_write2_b32 v177, v74, v75 offset1:1
	ds_write2_b32 v179, v76, v77 offset1:1
	ds_write2_b32 v194, v86, v87 offset1:1
	ds_write2_b32 v195, v88, v89 offset1:1
	ds_write2_b32 v196, v82, v83 offset1:1
	ds_write2_b32 v197, v84, v85 offset1:1
	ds_write2_b32 v198, v94, v95 offset1:1
	ds_write2_b32 v199, v96, v97 offset1:1
	ds_write2_b32 v200, v90, v91 offset1:1
	ds_write2_b32 v201, v92, v93 offset1:1
	ds_write2_b32 v202, v98, v99 offset1:1
	ds_write2_b32 v203, v100, v101 offset1:1
	ds_write2_b32 v204, v102, v103 offset1:1
	ds_write2_b32 v205, v104, v105 offset1:1
	ds_write2_b32 v206, v106, v107 offset1:1
	ds_write2_b32 v207, v108, v109 offset1:1
	ds_write2_b32 v208, v110, v111 offset1:1
	ds_write2_b32 v209, v112, v113 offset1:1
	ds_write2_b32 v210, v114, v115 offset1:1
	ds_write2_b32 v211, v116, v117 offset1:1
	ds_write2_b32 v212, v118, v119 offset1:1
	ds_write2_b32 v213, v120, v121 offset1:1
	ds_write2_b32 v214, v122, v123 offset1:1
	ds_write2_b32 v215, v124, v125 offset1:1
	ds_write2_b32 v216, v126, v127 offset1:1
	ds_write2_b32 v217, v128, v129 offset1:1
	v_cndmask_b32_e64 v130, 0, 1, vcc
	v_cmp_ne_u32_e64 s[6:7], 1, v130
	s_cbranch_scc1 .LBB0_189
	s_waitcnt lgkmcnt(0)
	v_mov_b32_e32 v156, 1.0
	s_and_b64 vcc, exec, s[6:7]
	v_mov_b32_e32 v130, 1.0
	v_mov_b32_e32 v131, 1.0
	v_mov_b32_e32 v132, 1.0
	v_mov_b32_e32 v133, 1.0
	v_mov_b32_e32 v134, 1.0
	v_mov_b32_e32 v135, 1.0
	v_mov_b32_e32 v136, 1.0
	v_mov_b32_e32 v137, 1.0
	s_cbranch_vccnz .LBB0_183
	v_lshlrev_b32_e32 v134, 2, v162
	v_readfirstlane_b32 s8, v190
	v_readfirstlane_b32 s9, v191
	s_nop 4
	global_load_dwordx4 v[130:133], v134, s[8:9] offset:16 nt
	s_nop 0
	global_load_dwordx4 v[134:137], v134, s[8:9] nt

.LBB0_224:
	s_waitcnt lgkmcnt(0)
	v_mov_b32_e32 v173, 1.0
	s_and_b64 vcc, exec, s[6:7]
	v_mov_b32_e32 v130, 1.0
	v_mov_b32_e32 v131, 1.0
	v_mov_b32_e32 v132, 1.0
	v_mov_b32_e32 v133, 1.0
	v_mov_b32_e32 v134, 1.0
	v_mov_b32_e32 v135, 1.0
	v_mov_b32_e32 v136, 1.0
	v_mov_b32_e32 v137, 1.0
	s_cbranch_vccnz .LBB0_226
	v_lshlrev_b32_e32 v134, 2, v162
	v_readfirstlane_b32 s6, v190
	v_readfirstlane_b32 s7, v191
	s_nop 4
	global_load_dwordx4 v[130:133], v134, s[6:7] offset:16 nt
	s_nop 0
	global_load_dwordx4 v[134:137], v134, s[6:7] nt

.LBB0_268:
	global_load_dwordx4 v[126:129], v[136:137], off offset:-4096 nt
	global_load_dwordx4 v[122:125], v[136:137], off offset:-3072 nt
	global_load_dwordx4 v[118:121], v[136:137], off offset:-2048 nt
	global_load_dwordx4 v[114:117], v[136:137], off offset:-1024 nt
	global_load_dwordx4 v[110:113], v[136:137], off nt
	global_load_dwordx4 v[106:109], v[136:137], off offset:1024 nt
	global_load_dwordx4 v[102:105], v[136:137], off offset:2048 nt
	global_load_dwordx4 v[98:101], v[136:137], off offset:3072 nt
	s_add_i32 s34, s76, s44
	s_cmpk_lt_i32 s34, 0x2000
	s_cselect_b64 s[40:41], -1, 0
	s_cmpk_gt_i32 s34, 0x1fff
	s_cbranch_scc1 .LBB0_270
	s_ashr_i32 s35, s34, 31
	s_lshl_b64 s[24:25], s[34:35], 13
	s_waitcnt vmcnt(9)
	v_lshl_add_u64 v[58:59], v[134:135], 0, s[24:25]
	global_load_dwordx4 v[46:49], v[58:59], off nt
	global_load_dwordx4 v[42:45], v[58:59], off offset:1024 nt
	global_load_dwordx4 v[38:41], v[58:59], off offset:2048 nt
	global_load_dwordx4 v[34:37], v[58:59], off offset:3072 nt
	v_add_co_u32_e32 v58, vcc, 0x1000, v58
	s_nop 1
	v_addc_co_u32_e32 v59, vcc, 0, v59, vcc
	global_load_dwordx4 v[70:73], v[58:59], off nt
	global_load_dwordx4 v[66:69], v[58:59], off offset:1024 nt
	global_load_dwordx4 v[62:65], v[58:59], off offset:2048 nt
	s_nop 0
	global_load_dwordx4 v[58:61], v[58:59], off offset:3072 nt
.LBB0_270:
	s_add_i32 s28, s43, s44
	s_cmpk_lt_i32 s28, 0x2000
	s_cselect_b64 s[30:31], -1, 0
	s_cmpk_gt_i32 s28, 0x1fff
	s_cbranch_scc1 .LBB0_272
	s_ashr_i32 s29, s28, 31
	s_lshl_b64 s[24:25], s[28:29], 13
	s_waitcnt vmcnt(19)
	v_lshl_add_u64 v[18:19], v[134:135], 0, s[24:25]
	global_load_dwordx4 v[14:17], v[18:19], off nt
	global_load_dwordx4 v[10:13], v[18:19], off offset:1024 nt
	global_load_dwordx4 v[6:9], v[18:19], off offset:2048 nt
	global_load_dwordx4 v[2:5], v[18:19], off offset:3072 nt
	v_add_co_u32_e32 v18, vcc, 0x1000, v18
	s_nop 1
	v_addc_co_u32_e32 v19, vcc, 0, v19, vcc
	global_load_dwordx4 v[30:33], v[18:19], off nt
	global_load_dwordx4 v[26:29], v[18:19], off offset:1024 nt
	global_load_dwordx4 v[22:25], v[18:19], off offset:2048 nt
	s_nop 0
	global_load_dwordx4 v[18:21], v[18:19], off offset:3072 nt
.LBB0_272:
	s_add_i32 s24, s42, s44
	s_cmpk_lt_i32 s24, 0x2000
	s_cselect_b64 s[26:27], -1, 0
	s_cmpk_gt_i32 s24, 0x1fff
	s_cbranch_scc1 .LBB0_274
	s_ashr_i32 s25, s24, 31
	s_lshl_b64 s[46:47], s[24:25], 13
	v_lshl_add_u64 v[82:83], v[134:135], 0, s[46:47]
	v_add_co_u32_e32 v94, vcc, 0x1000, v82
	global_load_dwordx4 v[50:53], v[82:83], off nt
	global_load_dwordx4 v[54:57], v[82:83], off offset:1024 nt
	global_load_dwordx4 v[74:77], v[82:83], off offset:2048 nt
	global_load_dwordx4 v[78:81], v[82:83], off offset:3072 nt
	v_addc_co_u32_e32 v95, vcc, 0, v83, vcc
	global_load_dwordx4 v[82:85], v[94:95], off nt
	global_load_dwordx4 v[86:89], v[94:95], off offset:1024 nt
	global_load_dwordx4 v[90:93], v[94:95], off offset:2048 nt
	s_nop 0
	global_load_dwordx4 v[94:97], v[94:95], off offset:3072 nt

.LBB0_284:
	global_load_dwordx4 v[126:129], v[140:141], off offset:-4096 nt
	global_load_dwordx4 v[122:125], v[140:141], off offset:-3072 nt
	global_load_dwordx4 v[118:121], v[140:141], off offset:-2048 nt
	global_load_dwordx4 v[114:117], v[140:141], off offset:-1024 nt
	global_load_dwordx4 v[110:113], v[140:141], off nt
	global_load_dwordx4 v[106:109], v[140:141], off offset:1024 nt
	global_load_dwordx4 v[102:105], v[140:141], off offset:2048 nt
	s_waitcnt lgkmcnt(0)
	global_load_dwordx4 v[98:101], v[140:141], off offset:3072 nt
	s_add_i32 s28, s76, s43
	s_cmpk_lt_i32 s28, 0x4000
	s_cselect_b64 s[34:35], -1, 0
	s_cmpk_gt_i32 s28, 0x3fff
	s_cbranch_scc1 .LBB0_286
	s_ashr_i32 s29, s28, 31
	s_lshl_b64 s[20:21], s[28:29], 13
	v_lshl_add_u64 v[82:83], v[132:133], 0, s[20:21]
	global_load_dwordx4 v[78:81], v[82:83], off nt
	global_load_dwordx4 v[74:77], v[82:83], off offset:1024 nt
	global_load_dwordx4 v[70:73], v[82:83], off offset:2048 nt
	global_load_dwordx4 v[66:69], v[82:83], off offset:3072 nt
	v_add_co_u32_e32 v82, vcc, 0x1000, v82
	s_nop 1
	v_addc_co_u32_e32 v83, vcc, 0, v83, vcc
	global_load_dwordx4 v[94:97], v[82:83], off nt
	global_load_dwordx4 v[90:93], v[82:83], off offset:1024 nt
	global_load_dwordx4 v[86:89], v[82:83], off offset:2048 nt
	s_nop 0
	global_load_dwordx4 v[82:85], v[82:83], off offset:3072 nt
.LBB0_286:
	s_add_i32 s24, s40, s43
	s_cmpk_lt_i32 s24, 0x4000
	s_cselect_b64 s[30:31], -1, 0
	s_cmpk_gt_i32 s24, 0x3fff
	s_cbranch_scc1 .LBB0_288
	s_ashr_i32 s25, s24, 31
	s_lshl_b64 s[20:21], s[24:25], 13
	s_waitcnt vmcnt(11)
	v_lshl_add_u64 v[50:51], v[132:133], 0, s[20:21]
	global_load_dwordx4 v[46:49], v[50:51], off nt
	global_load_dwordx4 v[42:45], v[50:51], off offset:1024 nt
	global_load_dwordx4 v[38:41], v[50:51], off offset:2048 nt
	global_load_dwordx4 v[34:37], v[50:51], off offset:3072 nt
	v_add_co_u32_e32 v50, vcc, 0x1000, v50
	s_nop 1
	v_addc_co_u32_e32 v51, vcc, 0, v51, vcc
	global_load_dwordx4 v[62:65], v[50:51], off nt
	global_load_dwordx4 v[58:61], v[50:51], off offset:1024 nt
	global_load_dwordx4 v[54:57], v[50:51], off offset:2048 nt
	s_nop 0
	global_load_dwordx4 v[50:53], v[50:51], off offset:3072 nt
.LBB0_288:
	s_add_i32 s20, s42, s43
	s_cmpk_lt_i32 s20, 0x4000
	s_cselect_b64 s[26:27], -1, 0
	s_cmpk_gt_i32 s20, 0x3fff
	s_cbranch_scc1 .LBB0_290
	s_ashr_i32 s21, s20, 31
	s_lshl_b64 s[36:37], s[20:21], 13
	s_waitcnt vmcnt(19)
	v_lshl_add_u64 v[18:19], v[132:133], 0, s[36:37]
	global_load_dwordx4 v[14:17], v[18:19], off nt
	global_load_dwordx4 v[10:13], v[18:19], off offset:1024 nt
	global_load_dwordx4 v[6:9], v[18:19], off offset:2048 nt
	global_load_dwordx4 v[2:5], v[18:19], off offset:3072 nt
	v_add_co_u32_e32 v18, vcc, 0x1000, v18
	s_nop 1
	v_addc_co_u32_e32 v19, vcc, 0, v19, vcc
	global_load_dwordx4 v[30:33], v[18:19], off nt
	global_load_dwordx4 v[26:29], v[18:19], off offset:1024 nt
	global_load_dwordx4 v[22:25], v[18:19], off offset:2048 nt
	s_nop 0
	global_load_dwordx4 v[18:21], v[18:19], off offset:3072 nt

.LBB0_305:
	global_load_dwordx4 v[28:31], v[16:17], off offset:-4096 nt
	global_load_dwordx4 v[32:35], v[16:17], off offset:-3072 nt
	global_load_dwordx4 v[36:39], v[16:17], off offset:-2048 nt
	global_load_dwordx4 v[40:43], v[16:17], off nt
	global_load_dwordx4 v[44:47], v[16:17], off offset:-1024 nt
	global_load_dwordx4 v[48:51], v[16:17], off offset:1024 nt
	global_load_dwordx4 v[52:55], v[16:17], off offset:2048 nt
	global_load_dwordx4 v[2:5], v[16:17], off offset:3072 nt
	global_load_dwordx4 v[56:59], v[6:7], off nt
	s_add_i32 s11, s11, s76
	v_lshl_add_u64 v[16:17], v[16:17], 0, s[6:7]
	s_cmpk_gt_i32 s11, 0x3ff
	s_waitcnt vmcnt(8)
	v_mov_b32_e32 v62, v29
	s_waitcnt vmcnt(7)
	v_mov_b32_e32 v63, v33
	v_mov_b32_e32 v66, v31
	v_mov_b32_e32 v67, v35
	v_mov_b32_e32 v60, v28
	v_mov_b32_e32 v61, v32
	v_mov_b32_e32 v64, v30
	v_mov_b32_e32 v65, v34
	s_waitcnt vmcnt(6)
	v_pk_mul_f32 v[68:69], v[38:39], v[38:39]
	v_pk_mul_f32 v[70:71], v[36:37], v[36:37]
	v_pk_mul_f32 v[62:63], v[62:63], v[62:63]
	v_pk_mul_f32 v[66:67], v[66:67], v[66:67]
	v_pk_mov_b32 v[84:85], v[70:71], v[68:69] op_sel:[1,0]
	v_mov_b32_e32 v71, v69
	v_pk_fma_f32 v[60:61], v[60:61], v[60:61], v[62:63]
	v_pk_fma_f32 v[62:63], v[64:65], v[64:65], v[66:67]
	s_waitcnt vmcnt(4)
	v_mul_f32_e32 v72, v45, v45
	v_mul_f32_e32 v74, v47, v47
	v_pk_add_f32 v[64:65], v[84:85], v[70:71]
	v_pk_add_f32 v[60:61], v[60:61], v[62:63]
	v_mul_f32_e32 v27, v40, v40
	v_mul_f32_e32 v83, v41, v41
	v_mul_f32_e32 v86, v42, v42
	v_mul_f32_e32 v87, v43, v43
	v_pk_fma_f32 v[68:69], v[44:45], v[44:45], v[72:73] op_sel_hi:[1,1,0]
	v_pk_fma_f32 v[72:73], v[46:47], v[46:47], v[74:75] op_sel_hi:[1,1,0]
	v_pk_add_f32 v[62:63], v[64:65], v[64:65] op_sel:[0,1] op_sel_hi:[1,0]
	v_pk_add_f32 v[60:61], v[60:61], v[60:61] op_sel:[0,1] op_sel_hi:[1,0]
	s_waitcnt vmcnt(3)
	v_pk_mul_f32 v[76:77], v[50:51], v[50:51]
	v_pk_mul_f32 v[78:79], v[48:49], v[48:49]
	v_mov_b32_e32 v69, v86
	v_mov_b32_e32 v73, v87
	v_mov_b32_e32 v63, v83
	v_mov_b32_e32 v61, v27
	v_pk_mov_b32 v[74:75], v[78:79], v[76:77] op_sel:[1,0]
	v_mov_b32_e32 v79, v77
	v_pk_add_f32 v[64:65], v[68:69], v[72:73]
	v_pk_add_f32 v[60:61], v[60:61], v[62:63]
	s_waitcnt vmcnt(2)
	v_mul_f32_e32 v80, v53, v53
	v_mul_f32_e32 v82, v55, v55
	v_pk_add_f32 v[66:67], v[74:75], v[78:79]
	v_pk_add_f32 v[60:61], v[60:61], v[64:65]
	s_waitcnt vmcnt(1)
	v_mul_f32_e32 v88, v2, v2
	v_mul_f32_e32 v89, v3, v3
	v_mul_f32_e32 v90, v4, v4
	v_mul_f32_e32 v91, v5, v5
	v_pk_fma_f32 v[76:77], v[52:53], v[52:53], v[80:81] op_sel_hi:[1,1,0]
	v_pk_fma_f32 v[80:81], v[54:55], v[54:55], v[82:83] op_sel_hi:[1,1,0]
	v_pk_add_f32 v[66:67], v[66:67], v[66:67] op_sel:[0,1] op_sel_hi:[1,0]
	v_pk_add_f32 v[60:61], v[60:61], v[60:61] op_sel:[0,1] op_sel_hi:[1,0]
	v_mov_b32_e32 v77, v90
	v_mov_b32_e32 v81, v91
	v_mov_b32_e32 v67, v89
	v_mov_b32_e32 v61, v88
	v_pk_add_f32 v[68:69], v[76:77], v[80:81]
	v_pk_add_f32 v[60:61], v[60:61], v[66:67]
	s_nop 0
	v_pk_add_f32 v[60:61], v[60:61], v[68:69]
	s_nop 0
	v_add_f32_e32 v27, v60, v61
	ds_bpermute_b32 v60, v20, v27
	s_waitcnt lgkmcnt(0)
	v_add_f32_e32 v27, v27, v60
	ds_bpermute_b32 v60, v21, v27
	s_waitcnt lgkmcnt(0)
	v_add_f32_e32 v27, v27, v60
	ds_bpermute_b32 v60, v22, v27
	s_waitcnt lgkmcnt(0)
	v_add_f32_e32 v27, v27, v60
	ds_bpermute_b32 v60, v23, v27
	s_waitcnt lgkmcnt(0)
	v_add_f32_e32 v27, v27, v60
	ds_bpermute_b32 v60, v24, v27
	s_waitcnt lgkmcnt(0)
	v_add_f32_e32 v27, v27, v60
	ds_bpermute_b32 v60, v25, v27
	s_waitcnt lgkmcnt(0)
	v_add_f32_e32 v27, v27, v60
	v_fmamk_f32 v27, v27, 0x3a000000, v26
	v_mul_f32_e32 v60, 0x4b800000, v27
	v_cmp_gt_f32_e32 vcc, s10, v27
	s_nop 1
	v_cndmask_b32_e32 v27, v27, v60, vcc
	v_rsq_f32_e32 v27, v27
	s_nop 0
	v_mul_f32_e32 v60, 0x45800000, v27
	v_cndmask_b32_e32 v60, v27, v60, vcc
	v_pk_mul_f32 v[28:29], v[28:29], v[60:61] op_sel_hi:[1,0]
	v_pk_mul_f32 v[30:31], v[30:31], v[60:61] op_sel_hi:[1,0]
	s_waitcnt vmcnt(0)
	v_pk_mul_f32 v[28:29], v[56:57], v[28:29]
	v_pk_mul_f32 v[30:31], v[58:59], v[30:31]
	v_cvt_pk_bf16_f32 v28, v28, v29
	v_pk_mul_f32 v[32:33], v[32:33], v[60:61] op_sel_hi:[1,0]
	v_cvt_pk_bf16_f32 v29, v30, v31
	global_store_dwordx2 v[18:19], v[28:29], off offset:-2048
	global_load_dwordx4 v[28:31], v[6:7], off offset:1024 nt
	v_pk_mul_f32 v[34:35], v[34:35], v[60:61] op_sel_hi:[1,0]
	v_pk_mul_f32 v[2:3], v[2:3], v[60:61] op_sel_hi:[1,0]
	v_pk_mul_f32 v[4:5], v[4:5], v[60:61] op_sel_hi:[1,0]
	s_waitcnt vmcnt(0)
	v_pk_mul_f32 v[28:29], v[28:29], v[32:33]
	v_pk_mul_f32 v[30:31], v[30:31], v[34:35]
	v_cvt_pk_bf16_f32 v28, v28, v29
	v_pk_mul_f32 v[32:33], v[36:37], v[60:61] op_sel_hi:[1,0]
	v_cvt_pk_bf16_f32 v29, v30, v31
	global_store_dwordx2 v[18:19], v[28:29], off offset:-1536
	global_load_dwordx4 v[28:31], v[6:7], off offset:2048 nt
	v_pk_mul_f32 v[34:35], v[38:39], v[60:61] op_sel_hi:[1,0]
	s_waitcnt vmcnt(0)
	v_pk_mul_f32 v[28:29], v[28:29], v[32:33]
	v_pk_mul_f32 v[30:31], v[30:31], v[34:35]
	v_cvt_pk_bf16_f32 v28, v28, v29
	v_pk_mul_f32 v[32:33], v[44:45], v[60:61] op_sel_hi:[1,0]
	v_cvt_pk_bf16_f32 v29, v30, v31
	global_store_dwordx2 v[18:19], v[28:29], off offset:-1024
	global_load_dwordx4 v[28:31], v[6:7], off offset:3072 nt
	v_pk_mul_f32 v[34:35], v[46:47], v[60:61] op_sel_hi:[1,0]
	s_waitcnt vmcnt(0)
	v_pk_mul_f32 v[28:29], v[28:29], v[32:33]
	v_pk_mul_f32 v[30:31], v[30:31], v[34:35]
	v_cvt_pk_bf16_f32 v28, v28, v29
	v_pk_mul_f32 v[32:33], v[40:41], v[60:61] op_sel_hi:[1,0]
	v_cvt_pk_bf16_f32 v29, v30, v31
	global_store_dwordx2 v[18:19], v[28:29], off offset:-512
	global_load_dwordx4 v[28:31], v[8:9], off nt
	v_pk_mul_f32 v[34:35], v[42:43], v[60:61] op_sel_hi:[1,0]
	s_waitcnt vmcnt(0)
	v_pk_mul_f32 v[28:29], v[32:33], v[28:29]
	v_pk_mul_f32 v[30:31], v[34:35], v[30:31]
	v_cvt_pk_bf16_f32 v28, v28, v29
	v_pk_mul_f32 v[32:33], v[48:49], v[60:61] op_sel_hi:[1,0]
	v_cvt_pk_bf16_f32 v29, v30, v31
	global_store_dwordx2 v[18:19], v[28:29], off
	global_load_dwordx4 v[28:31], v[10:11], off nt
	v_pk_mul_f32 v[34:35], v[50:51], v[60:61] op_sel_hi:[1,0]
	s_waitcnt vmcnt(0)
	v_pk_mul_f32 v[28:29], v[32:33], v[28:29]
	v_pk_mul_f32 v[30:31], v[34:35], v[30:31]
	v_cvt_pk_bf16_f32 v28, v28, v29
	v_pk_mul_f32 v[32:33], v[52:53], v[60:61] op_sel_hi:[1,0]
	v_cvt_pk_bf16_f32 v29, v30, v31
	global_store_dwordx2 v[18:19], v[28:29], off offset:512
	global_load_dwordx4 v[28:31], v[12:13], off nt
	v_pk_mul_f32 v[34:35], v[54:55], v[60:61] op_sel_hi:[1,0]
	s_waitcnt vmcnt(0)
	v_pk_mul_f32 v[28:29], v[32:33], v[28:29]
	v_pk_mul_f32 v[30:31], v[34:35], v[30:31]
	v_cvt_pk_bf16_f32 v28, v28, v29
	s_nop 0
	v_cvt_pk_bf16_f32 v29, v30, v31
	global_store_dwordx2 v[18:19], v[28:29], off offset:1024
	global_load_dwordx4 v[28:31], v[14:15], off nt
	s_waitcnt vmcnt(0)
	v_pk_mul_f32 v[2:3], v[2:3], v[28:29]
	v_pk_mul_f32 v[4:5], v[4:5], v[30:31]
	v_cvt_pk_bf16_f32 v2, v2, v3
	s_nop 0
	v_cvt_pk_bf16_f32 v3, v4, v5
	global_store_dwordx2 v[18:19], v[2:3], off offset:1536
	v_lshl_add_u64 v[18:19], v[18:19], 0, s[8:9]
	s_cbranch_scc0 .LBB0_305
